# grid barrier: middle arrivers (16 / 4 still to come) start an L2 writeback while they wait
# speedup vs baseline: 1.0111x; 1.0111x over previous
.LBB0_185:
	s_or_b64 exec, exec, s[14:15]
	v_cvt_f32_u32_e32 v4, v2
	s_waitcnt vmcnt(0)
	v_readfirstlane_b32 s4, v3
	v_sub_u32_e32 v3, 0, v2
	v_rcp_iflag_f32_e32 v4, v4
	v_add_u32_e32 v5, s4, v0
	v_mul_f32_e32 v4, 0x4f7ffffe, v4
	v_cvt_u32_f32_e32 v4, v4
	v_mul_lo_u32 v0, v3, v4
	v_mul_hi_u32 v0, v4, v0
	v_add_u32_e32 v0, v4, v0
	v_mul_hi_u32 v0, v5, v0
	v_mul_lo_u32 v3, v0, v2
	v_sub_u32_e32 v3, v5, v3
	v_add_u32_e32 v4, 1, v0
	v_cmp_ge_u32_e32 vcc, v3, v2
	s_nop 1
	v_cndmask_b32_e32 v0, v0, v4, vcc
	v_sub_u32_e32 v4, v3, v2
	v_cndmask_b32_e32 v3, v3, v4, vcc
	v_add_u32_e32 v4, 1, v0
	v_cmp_ge_u32_e32 vcc, v3, v2
	v_add_u32_e32 v3, 1, v5
	s_nop 0
	v_cndmask_b32_e32 v0, v0, v4, vcc
	v_mul_lo_u32 v4, v2, v0
	v_add_u32_e32 v2, v4, v2
	v_cmp_ne_u32_e32 vcc, v3, v2
	s_and_saveexec_b64 s[4:5], vcc
	s_xor_b64 s[12:13], exec, s[4:5]
	s_cbranch_execz .LBB0_199
	s_waitcnt lgkmcnt(0)
	v_sub_u32_e32 v4, v2, v3
	v_cmp_eq_u32_e32 vcc, 16, v4
	s_cbranch_vccnz .Lxbw_do_0
	v_cmp_eq_u32_e32 vcc, 4, v4
	s_cbranch_vccz .Lxbw_skip_0
.Lxbw_do_0:
	buffer_wbl2 sc1
.Lxbw_skip_0:
	v_mov_b32_e32 v1, 0x2000
	global_load_dword v1, v1, s[8:9] offset:1024 sc1
	s_add_u32 s18, s8, 0x2400
	s_addc_u32 s19, s9, 0
	s_waitcnt vmcnt(0)
	v_cmp_eq_u32_e32 vcc, v1, v0
	s_and_saveexec_b64 s[14:15], vcc
	s_cbranch_execz .LBB0_198
	s_add_u32 s16, s30, 0x24400200
	s_addc_u32 s17, s31, 0
	s_mov_b32 s4, 1
	s_mov_b64 s[22:23], 0
	v_mov_b32_e32 v1, 0
	s_branch .LBB0_189

.LBB0_261:
	s_or_b64 exec, exec, s[16:17]
	v_cvt_f32_u32_e32 v4, v2
	s_waitcnt vmcnt(0)
	v_readfirstlane_b32 s4, v3
	v_sub_u32_e32 v3, 0, v2
	v_rcp_iflag_f32_e32 v4, v4
	v_add_u32_e32 v5, s4, v0
	v_mul_f32_e32 v4, 0x4f7ffffe, v4
	v_cvt_u32_f32_e32 v4, v4
	v_mul_lo_u32 v0, v3, v4
	v_mul_hi_u32 v0, v4, v0
	v_add_u32_e32 v0, v4, v0
	v_mul_hi_u32 v0, v5, v0
	v_mul_lo_u32 v3, v0, v2
	v_sub_u32_e32 v3, v5, v3
	v_add_u32_e32 v4, 1, v0
	v_cmp_ge_u32_e32 vcc, v3, v2
	s_nop 1
	v_cndmask_b32_e32 v0, v0, v4, vcc
	v_sub_u32_e32 v4, v3, v2
	v_cndmask_b32_e32 v3, v3, v4, vcc
	v_add_u32_e32 v4, 1, v0
	v_cmp_ge_u32_e32 vcc, v3, v2
	v_add_u32_e32 v3, 1, v5
	s_nop 0
	v_cndmask_b32_e32 v0, v0, v4, vcc
	v_mul_lo_u32 v4, v2, v0
	v_add_u32_e32 v2, v4, v2
	v_cmp_ne_u32_e32 vcc, v3, v2
	s_and_saveexec_b64 s[4:5], vcc
	s_xor_b64 s[14:15], exec, s[4:5]
	s_cbranch_execz .LBB0_275
	s_waitcnt lgkmcnt(0)
	v_sub_u32_e32 v4, v2, v3
	v_cmp_eq_u32_e32 vcc, 16, v4
	s_cbranch_vccnz .Lxbw_do_1
	v_cmp_eq_u32_e32 vcc, 4, v4
	s_cbranch_vccz .Lxbw_skip_1

.Lxbw_skip_1:
	v_mov_b32_e32 v1, 0x2000
	global_load_dword v1, v1, s[8:9] offset:1024 sc1
	s_add_u32 s22, s8, 0x2400
	s_addc_u32 s23, s9, 0
	s_waitcnt vmcnt(0)
	v_cmp_eq_u32_e32 vcc, v1, v0
	s_and_saveexec_b64 s[16:17], vcc
	s_cbranch_execz .LBB0_274
	s_add_u32 s18, s30, 0x24400200
	s_addc_u32 s19, s31, 0
	s_mov_b32 s4, 1
	s_mov_b64 s[24:25], 0
	v_mov_b32_e32 v1, 0
	s_branch .LBB0_265

.Lxbw_skip_3:
	v_mov_b32_e32 v1, 0x2000
	global_load_dword v1, v1, s[12:13] offset:1024 sc1
	s_add_u32 s20, s12, 0x2400
	s_addc_u32 s21, s13, 0
	s_waitcnt vmcnt(0)
	v_cmp_eq_u32_e32 vcc, v1, v0
	s_and_saveexec_b64 s[16:17], vcc
	s_cbranch_execz .LBB0_419
	s_add_u32 s18, s30, 0x24400200
	s_addc_u32 s19, s31, 0
	s_mov_b32 s4, 1
	s_mov_b64 s[22:23], 0
	v_mov_b32_e32 v1, 0
	s_branch .LBB0_410

.LBB0_786:
	s_or_b64 exec, exec, s[18:19]
	v_cvt_f32_u32_e32 v4, v2
	s_waitcnt vmcnt(0)
	v_readfirstlane_b32 s4, v3
	v_sub_u32_e32 v3, 0, v2
	v_rcp_iflag_f32_e32 v4, v4
	v_add_u32_e32 v5, s4, v0
	v_mul_f32_e32 v4, 0x4f7ffffe, v4
	v_cvt_u32_f32_e32 v4, v4
	v_mul_lo_u32 v0, v3, v4
	v_mul_hi_u32 v0, v4, v0
	v_add_u32_e32 v0, v4, v0
	v_mul_hi_u32 v0, v5, v0
	v_mul_lo_u32 v3, v0, v2
	v_sub_u32_e32 v3, v5, v3
	v_add_u32_e32 v4, 1, v0
	v_cmp_ge_u32_e32 vcc, v3, v2
	s_nop 1
	v_cndmask_b32_e32 v0, v0, v4, vcc
	v_sub_u32_e32 v4, v3, v2
	v_cndmask_b32_e32 v3, v3, v4, vcc
	v_add_u32_e32 v4, 1, v0
	v_cmp_ge_u32_e32 vcc, v3, v2
	v_add_u32_e32 v3, 1, v5
	s_nop 0
	v_cndmask_b32_e32 v0, v0, v4, vcc
	v_mul_lo_u32 v4, v2, v0
	v_add_u32_e32 v2, v4, v2
	v_cmp_ne_u32_e32 vcc, v3, v2
	s_and_saveexec_b64 s[4:5], vcc
	s_xor_b64 s[16:17], exec, s[4:5]
	s_cbranch_execz .LBB0_800
	s_waitcnt lgkmcnt(0)
	v_sub_u32_e32 v4, v2, v3
	v_cmp_eq_u32_e32 vcc, 16, v4
	s_cbranch_vccnz .Lxbw_do_6
	v_cmp_eq_u32_e32 vcc, 4, v4
	s_cbranch_vccz .Lxbw_skip_6

.Lxbw_skip_6:
	v_mov_b32_e32 v1, 0x2000
	global_load_dword v1, v1, s[14:15] offset:1024 sc1
	s_add_u32 s60, s14, 0x2400
	s_addc_u32 s61, s15, 0
	s_waitcnt vmcnt(0)
	v_cmp_eq_u32_e32 vcc, v1, v0
	s_and_saveexec_b64 s[18:19], vcc
	s_cbranch_execz .LBB0_799
	s_add_u32 s20, s30, 0x24400200
	s_addc_u32 s21, s31, 0
	s_mov_b32 s4, 1
	s_mov_b64 s[62:63], 0
	v_mov_b32_e32 v1, 0
	s_branch .LBB0_790

.Lxbw_skip_11:
	v_mov_b32_e32 v1, 0x2000
	global_load_dword v1, v1, s[10:11] offset:1024 sc1
	s_add_u32 s18, s10, 0x2400
	s_addc_u32 s19, s11, 0
	s_waitcnt vmcnt(0)
	v_cmp_eq_u32_e32 vcc, v1, v0
	s_and_saveexec_b64 s[14:15], vcc
	s_cbranch_execz .LBB0_1584
	s_add_u32 s16, s30, 0x24400200
	s_addc_u32 s17, s31, 0
	s_mov_b32 s4, 1
	s_mov_b64 s[20:21], 0
	v_mov_b32_e32 v1, 0
	s_branch .LBB0_1575

.Lxbw_skip_14:
	v_mov_b32_e32 v1, 0x2000
	global_load_dword v1, v1, s[10:11] offset:1024 sc1
	s_add_u32 s20, s10, 0x2400
	s_addc_u32 s21, s11, 0
	s_waitcnt vmcnt(0)
	v_cmp_eq_u32_e32 vcc, v1, v0
	s_and_saveexec_b64 s[14:15], vcc
	s_cbranch_execz .LBB0_1836
	s_add_u32 s18, s30, 0x24400200
	s_addc_u32 s19, s31, 0
	s_mov_b32 s4, 1
	s_mov_b64 s[22:23], 0
	v_mov_b32_e32 v1, 0
	s_branch .LBB0_1827

.LBB0_1931:
	s_or_b64 exec, exec, s[10:11]
	v_cvt_f32_u32_e32 v4, v2
	s_waitcnt vmcnt(0)
	v_readfirstlane_b32 s8, v3
	v_sub_u32_e32 v3, 0, v2
	v_rcp_iflag_f32_e32 v4, v4
	v_add_u32_e32 v5, s8, v0
	v_mul_f32_e32 v4, 0x4f7ffffe, v4
	v_cvt_u32_f32_e32 v4, v4
	v_mul_lo_u32 v0, v3, v4
	v_mul_hi_u32 v0, v4, v0
	v_add_u32_e32 v0, v4, v0
	v_mul_hi_u32 v0, v5, v0
	v_mul_lo_u32 v3, v0, v2
	v_sub_u32_e32 v3, v5, v3
	v_add_u32_e32 v4, 1, v0
	v_cmp_ge_u32_e32 vcc, v3, v2
	s_nop 1
	v_cndmask_b32_e32 v0, v0, v4, vcc
	v_sub_u32_e32 v4, v3, v2
	v_cndmask_b32_e32 v3, v3, v4, vcc
	v_add_u32_e32 v4, 1, v0
	v_cmp_ge_u32_e32 vcc, v3, v2
	v_add_u32_e32 v3, 1, v5
	s_nop 0
	v_cndmask_b32_e32 v0, v0, v4, vcc
	v_mul_lo_u32 v4, v2, v0
	v_add_u32_e32 v2, v4, v2
	v_cmp_ne_u32_e32 vcc, v3, v2
	s_and_saveexec_b64 s[8:9], vcc
	s_xor_b64 s[8:9], exec, s[8:9]
	s_cbranch_execz .LBB0_1945
	s_waitcnt lgkmcnt(0)
	v_sub_u32_e32 v4, v2, v3
	v_cmp_eq_u32_e32 vcc, 16, v4
	s_cbranch_vccnz .Lxbw_do_15
	v_cmp_eq_u32_e32 vcc, 4, v4
	s_cbranch_vccz .Lxbw_skip_15

.Lxbw_skip_15:
	v_mov_b32_e32 v1, 0x2000
	global_load_dword v1, v1, s[4:5] offset:1024 sc1
	s_add_u32 s14, s4, 0x2400
	s_addc_u32 s15, s5, 0
	s_waitcnt vmcnt(0)
	v_cmp_eq_u32_e32 vcc, v1, v0
	s_and_saveexec_b64 s[10:11], vcc
	s_cbranch_execz .LBB0_1944
	s_add_u32 s12, s30, 0x24400200
	s_addc_u32 s13, s31, 0
	s_mov_b32 s33, 1
	s_mov_b64 s[16:17], 0
	v_mov_b32_e32 v1, 0
	s_branch .LBB0_1935
